# residual-add GEMM epilogue: all four row-batches of the f32 residual prefetched at the start of each pass (counted vmcnt), instead of one exposed round trip per batch
# baseline (speedup 1.0000x reference)
; DI void gemm_tile(const GD& g, int pm, int pn, bf16_t* shm) {
;     ...
;       const int c4 = (lane & 15) * 4;
;       const int gcol = bcol + ((c4 >= 32) ? HALF : 0) + wc * 32 + (c4 & 31);
;       float4 gn = make_float4(0.f, 0.f, 0.f, 0.f);
;       if (g.epi == 1 && g.gnext) gn = *reinterpret_cast<const float4*>(g.gnext + gcol);
; #pragma unroll
;       for (int pb8 = 0; pb8 < 4; ++pb8) {
;         float4 xs[4];
;         if (g.epi == 1) {
; #pragma unroll
;           for (int q = 0; q < 4; ++q) {
;             const int grow = brow + ai * HALF + wr * 64 + (pb8 * 4 + q) * 4 + (lane >> 4);
;             xs[q] = *reinterpret_cast<const float4*>((const float*)g.C + (long)grow * ldc + gcol);
;           }
;         }
.LBB0_617:
	v_or_b32_e32 v2, s18, v138
	s_lshl_b32 s0, s49, 2
	v_mad_u32_u24 v100, v151, 12, v152
	v_add_u32_e32 v98, s24, v0
	s_ashr_i32 s1, s0, 31
	s_andn2_b64 vcc, exec, s[2:3]
	v_add_u32_e32 v99, v2, v154
	s_cbranch_vccnz .LBB0_882
	s_cmp_eq_u32 s48, 1
	v_ashrrev_i32_e32 v0, 31, v99
	s_cselect_b64 s[54:55], -1, 0
	s_cmp_lg_u32 s48, 1
	v_mul_lo_u32 v102, v0, s78
	s_cbranch_scc1 .LBB0_620
	v_or_b32_e32 v0, 4, v99
	v_mad_u64_u32 v[4:5], s[2:3], v99, s78, 0
	v_mad_u64_u32 v[6:7], s[2:3], v0, s78, 0
	v_lshl_add_u64 v[2:3], v[94:95], 2, s[34:35]
	v_add_u32_e32 v5, v5, v102
	v_add_u32_e32 v7, v7, v102
	v_lshl_add_u64 v[4:5], v[4:5], 2, v[2:3]
	v_lshl_add_u64 v[6:7], v[6:7], 2, v[2:3]
	v_or_b32_e32 v0, 8, v99
	global_load_dwordx4 v[14:17], v[4:5], off
	s_nop 0
	global_load_dwordx4 v[6:9], v[6:7], off
	v_mad_u64_u32 v[4:5], s[2:3], v0, s78, 0
	v_or_b32_e32 v0, 12, v99
	v_mad_u64_u32 v[10:11], s[2:3], v0, s78, 0
	v_add_u32_e32 v5, v5, v102
	v_add_u32_e32 v11, v11, v102
	v_lshl_add_u64 v[4:5], v[4:5], 2, v[2:3]
	v_lshl_add_u64 v[2:3], v[10:11], 2, v[2:3]
	global_load_dwordx4 v[10:13], v[4:5], off
	s_nop 0
	global_load_dwordx4 v[2:5], v[2:3], off
	v_lshl_add_u64 v[194:195], v[94:95], 2, s[34:35]
	v_add_u32_e32 v196, 16, v99
	v_mad_u64_u32 v[198:199], s[2:3], v196, s78, 0
	v_lshl_add_u64 v[198:199], v[198:199], 2, v[194:195]
	global_load_dwordx4 v[108:111], v[198:199], off
	v_add_u32_e32 v196, 20, v99
	v_mad_u64_u32 v[198:199], s[2:3], v196, s78, 0
	v_lshl_add_u64 v[198:199], v[198:199], 2, v[194:195]
	global_load_dwordx4 v[112:115], v[198:199], off
	v_add_u32_e32 v196, 24, v99
	v_mad_u64_u32 v[198:199], s[2:3], v196, s78, 0
	v_lshl_add_u64 v[198:199], v[198:199], 2, v[194:195]
	global_load_dwordx4 v[116:119], v[198:199], off
	v_add_u32_e32 v196, 28, v99
	v_mad_u64_u32 v[198:199], s[2:3], v196, s78, 0
	v_lshl_add_u64 v[198:199], v[198:199], 2, v[194:195]
	global_load_dwordx4 v[120:123], v[198:199], off
	v_add_u32_e32 v196, 32, v99
	v_mad_u64_u32 v[198:199], s[2:3], v196, s78, 0
	v_lshl_add_u64 v[198:199], v[198:199], 2, v[194:195]
	global_load_dwordx4 v[124:127], v[198:199], off
	v_add_u32_e32 v196, 36, v99
	v_mad_u64_u32 v[198:199], s[2:3], v196, s78, 0
	v_lshl_add_u64 v[198:199], v[198:199], 2, v[194:195]
	global_load_dwordx4 v[156:159], v[198:199], off
	v_add_u32_e32 v196, 40, v99
	v_mad_u64_u32 v[198:199], s[2:3], v196, s78, 0
	v_lshl_add_u64 v[198:199], v[198:199], 2, v[194:195]
	global_load_dwordx4 v[160:163], v[198:199], off
	v_add_u32_e32 v196, 44, v99
	v_mad_u64_u32 v[198:199], s[2:3], v196, s78, 0
	v_lshl_add_u64 v[198:199], v[198:199], 2, v[194:195]
	global_load_dwordx4 v[164:167], v[198:199], off
	v_add_u32_e32 v196, 48, v99
	v_mad_u64_u32 v[198:199], s[2:3], v196, s78, 0
	v_lshl_add_u64 v[198:199], v[198:199], 2, v[194:195]
	global_load_dwordx4 v[168:171], v[198:199], off
	v_add_u32_e32 v196, 52, v99
	v_mad_u64_u32 v[198:199], s[2:3], v196, s78, 0
	v_lshl_add_u64 v[198:199], v[198:199], 2, v[194:195]
	global_load_dwordx4 v[172:175], v[198:199], off
	v_add_u32_e32 v196, 56, v99
	v_mad_u64_u32 v[198:199], s[2:3], v196, s78, 0
	v_lshl_add_u64 v[198:199], v[198:199], 2, v[194:195]
	global_load_dwordx4 v[176:179], v[198:199], off
	v_add_u32_e32 v196, 60, v99
	v_mad_u64_u32 v[198:199], s[2:3], v196, s78, 0
	v_lshl_add_u64 v[198:199], v[198:199], 2, v[194:195]
	global_load_dwordx4 v[180:183], v[198:199], off

; DI unsigned pk2(float a, float b) { f32x2 v; v[0] = a; v[1] = b; return __builtin_bit_cast(unsigned, __builtin_convertvector(v, bf16v2)); }
; DI float shx_(float v, int m) { return __int_as_float(__builtin_amdgcn_ds_bpermute((lane_pinned_() ^ m) << 2, __float_as_int(v))); }
; DI int shx_(int v, int m) { return __builtin_amdgcn_ds_bpermute((lane_pinned_() ^ m) << 2, v); }
; DI void gemm_tile(const GD& g, int pm, int pn, bf16_t* shm) {
;     ...
;         for (int q = 0; q < 4; ++q) {
;           const int row_l = (pb8 * 4 + q) * 4 + (lane >> 4);
;           float4 v = *reinterpret_cast<const float4*>(stgw + row_l * 68 + c4);
;           const int grow = brow + ai * HALF + wr * 64 + row_l;
;           if (g.epi == 0) {
;             if (g.rowscale) {
;               const float rr = rsc[ai * HALF + wr * 64 + row_l];
;               v.x *= rr; v.y *= rr; v.z *= rr; v.w *= rr;
;             }
;             u32x2 o2; o2[0] = pk2(v.x, v.y); o2[1] = pk2(v.z, v.w);
;             *reinterpret_cast<u32x2*>((bf16_t*)g.C + (long)grow * ldc + gcol) = o2;
;           } else if (g.epi == 2) {
;             const float rr = rsc[ai * HALF + wr * 64 + row_l];
;             v.x *= rr; v.y *= rr; v.z *= rr; v.w *= rr;
;             *reinterpret_cast<float4*>((float*)g.C + (long)grow * ldc + gcol) = v;
;           } else {
;             float4 x = xs[q];
;             x.x += v.x; x.y += v.y; x.z += v.z; x.w += v.w;
;             *reinterpret_cast<float4*>((float*)g.C + (long)grow * ldc + gcol) = x;
;             if (g.gnext) {
;               u32x2 o2; o2[0] = pk2(x.x * gn.x, x.y * gn.y); o2[1] = pk2(x.z * gn.z, x.w * gn.w);
;               *reinterpret_cast<u32x2*>(g.hbout + (long)grow * DM + gcol) = o2;
;               float sq = (x.x * x.x + x.y * x.y) + (x.z * x.z + x.w * x.w);
;               sq += shx_(sq, 1); sq += shx_(sq, 2); sq += shx_(sq, 4); sq += shx_(sq, 8);
;               if ((lane & 15) == 0) g.ss[(long)grow * 32 + pn * 4 + wc] = sq;
;             }
.LBB0_625:
	v_mad_u64_u32 v[104:105], s[2:3], v96, s78, 0
	v_mov_b32_e32 v0, v105
	v_mad_u64_u32 v[106:107], s[2:3], v97, s78, v[0:1]
	v_mov_b32_e32 v105, v106
	v_lshl_add_u64 v[104:105], v[104:105], 2, s[34:35]
	s_waitcnt vmcnt(12) lgkmcnt(0)
	v_pk_add_f32 v[90:91], v[14:15], v[86:87]
	v_pk_add_f32 v[92:93], v[16:17], v[88:89]
	v_lshl_add_u64 v[104:105], v[94:95], 2, v[104:105]
	s_cmp_eq_u64 s[80:81], 0
	global_store_dwordx4 v[104:105], v[90:93], off
	s_cbranch_scc1 .LBB0_629
	v_pk_mul_f32 v[104:105], v[82:83], v[90:91]
	v_pk_mul_f32 v[106:107], v[84:85], v[92:93]
	v_cvt_pk_bf16_f32 v104, v104, v105
	v_cvt_pk_bf16_f32 v105, v106, v107
	v_lshlrev_b64 v[106:107], 12, v[96:97]
	v_pk_mul_f32 v[90:91], v[90:91], v[90:91]
	v_pk_mul_f32 v[92:93], v[92:93], v[92:93]
	v_lshl_add_u64 v[106:107], s[20:21], 0, v[106:107]
	v_add_f32_e32 v0, v92, v93
	v_add_f32_e32 v90, v90, v91
	v_lshl_add_u64 v[106:107], v[94:95], 1, v[106:107]
	v_add_f32_e32 v0, v90, v0
	global_store_dwordx2 v[106:107], v[104:105], off
	s_nop 1
	v_mov_b32_dpp v90, v0 quad_perm:[1,0,3,2] row_mask:0xf bank_mask:0xf
	s_waitcnt lgkmcnt(0)
	v_add_f32_e32 v0, v0, v90
	s_nop 1
	v_mov_b32_dpp v90, v0 quad_perm:[2,3,0,1] row_mask:0xf bank_mask:0xf
	s_waitcnt lgkmcnt(0)
	v_add_f32_e32 v0, v0, v90
	s_nop 1
	v_mov_b32_dpp v90, v0 row_half_mirror row_mask:0xf bank_mask:0xf
	s_waitcnt lgkmcnt(0)
	v_add_f32_e32 v90, v0, v90
	s_nop 1
	v_mov_b32_dpp v91, v90 row_ror:8 row_mask:0xf bank_mask:0xf
	s_and_saveexec_b64 s[2:3], s[4:5]
	s_cbranch_execz .LBB0_628
	v_lshlrev_b64 v[92:93], 7, v[96:97]
	v_lshl_add_u64 v[92:93], s[42:43], 0, v[92:93]
	v_lshl_add_u64 v[92:93], s[0:1], 2, v[92:93]
	v_lshlrev_b32_e32 v0, 2, v139
	v_lshl_add_u64 v[92:93], v[92:93], 0, v[0:1]
	s_waitcnt lgkmcnt(0)
	v_add_f32_e32 v0, v90, v91
	global_store_dword v[92:93], v0, off

; DI void gemm_tile(const GD& g, int pm, int pn, bf16_t* shm) {
;     ...
;       for (int pb8 = 0; pb8 < 4; ++pb8) {
;         float4 xs[4];
;         if (g.epi == 1) {
; #pragma unroll
;           for (int q = 0; q < 4; ++q) {
;             const int grow = brow + ai * HALF + wr * 64 + (pb8 * 4 + q) * 4 + (lane >> 4);
;             xs[q] = *reinterpret_cast<const float4*>((const float*)g.C + (long)grow * ldc + gcol);
;           }
;         }
.LBB0_679:
	v_or_b32_e32 v0, 16, v99
	v_mad_u64_u32 v[4:5], s[2:3], v0, s78, 0
	v_or_b32_e32 v0, 20, v99
	v_mad_u64_u32 v[6:7], s[2:3], v0, s78, 0
	v_lshl_add_u64 v[2:3], v[94:95], 2, s[34:35]
	v_add_u32_e32 v5, v5, v102
	v_add_u32_e32 v7, v7, v102
	v_lshl_add_u64 v[4:5], v[4:5], 2, v[2:3]
	v_lshl_add_u64 v[6:7], v[6:7], 2, v[2:3]
	v_or_b32_e32 v0, 24, v99
	s_nop 0
	v_mad_u64_u32 v[4:5], s[2:3], v0, s78, 0
	v_or_b32_e32 v0, 28, v99
	v_mad_u64_u32 v[10:11], s[2:3], v0, s78, 0
	v_add_u32_e32 v5, v5, v102
	v_add_u32_e32 v11, v11, v102
	v_lshl_add_u64 v[4:5], v[4:5], 2, v[2:3]
	v_lshl_add_u64 v[2:3], v[10:11], 2, v[2:3]
	s_nop 0
	s_waitcnt vmcnt(12)
	v_mov_b64_e32 v[14:15], v[108:109]
	v_mov_b64_e32 v[16:17], v[110:111]
	v_mov_b64_e32 v[6:7], v[112:113]
	v_mov_b64_e32 v[8:9], v[114:115]
	v_mov_b64_e32 v[10:11], v[116:117]
	v_mov_b64_e32 v[12:13], v[118:119]
	v_mov_b64_e32 v[2:3], v[120:121]
	v_mov_b64_e32 v[4:5], v[122:123]

; DI unsigned pk2(float a, float b) { f32x2 v; v[0] = a; v[1] = b; return __builtin_bit_cast(unsigned, __builtin_convertvector(v, bf16v2)); }
; DI float shx_(float v, int m) { return __int_as_float(__builtin_amdgcn_ds_bpermute((lane_pinned_() ^ m) << 2, __float_as_int(v))); }
; DI int shx_(int v, int m) { return __builtin_amdgcn_ds_bpermute((lane_pinned_() ^ m) << 2, v); }
; DI void gemm_tile(const GD& g, int pm, int pn, bf16_t* shm) {
;     ...
;         for (int q = 0; q < 4; ++q) {
;           const int row_l = (pb8 * 4 + q) * 4 + (lane >> 4);
;           float4 v = *reinterpret_cast<const float4*>(stgw + row_l * 68 + c4);
;           const int grow = brow + ai * HALF + wr * 64 + row_l;
;           if (g.epi == 0) {
;             if (g.rowscale) {
;               const float rr = rsc[ai * HALF + wr * 64 + row_l];
;               v.x *= rr; v.y *= rr; v.z *= rr; v.w *= rr;
;             }
;             u32x2 o2; o2[0] = pk2(v.x, v.y); o2[1] = pk2(v.z, v.w);
;             *reinterpret_cast<u32x2*>((bf16_t*)g.C + (long)grow * ldc + gcol) = o2;
;           } else if (g.epi == 2) {
;             const float rr = rsc[ai * HALF + wr * 64 + row_l];
;             v.x *= rr; v.y *= rr; v.z *= rr; v.w *= rr;
;             *reinterpret_cast<float4*>((float*)g.C + (long)grow * ldc + gcol) = v;
;           } else {
;             float4 x = xs[q];
;             x.x += v.x; x.y += v.y; x.z += v.z; x.w += v.w;
;             *reinterpret_cast<float4*>((float*)g.C + (long)grow * ldc + gcol) = x;
;             if (g.gnext) {
;               u32x2 o2; o2[0] = pk2(x.x * gn.x, x.y * gn.y); o2[1] = pk2(x.z * gn.z, x.w * gn.w);
;               *reinterpret_cast<u32x2*>(g.hbout + (long)grow * DM + gcol) = o2;
;               float sq = (x.x * x.x + x.y * x.y) + (x.z * x.z + x.w * x.w);
;               sq += shx_(sq, 1); sq += shx_(sq, 2); sq += shx_(sq, 4); sq += shx_(sq, 8);
;               if ((lane & 15) == 0) g.ss[(long)grow * 32 + pn * 4 + wc] = sq;
;             }
.LBB0_685:
	v_mad_u64_u32 v[104:105], s[2:3], v96, s78, 0
	v_mov_b32_e32 v0, v105
	v_mad_u64_u32 v[106:107], s[2:3], v97, s78, v[0:1]
	v_mov_b32_e32 v105, v106
	v_lshl_add_u64 v[104:105], v[104:105], 2, s[34:35]
	s_waitcnt lgkmcnt(0)
	v_pk_add_f32 v[90:91], v[14:15], v[86:87]
	v_pk_add_f32 v[92:93], v[16:17], v[88:89]
	v_lshl_add_u64 v[104:105], v[94:95], 2, v[104:105]
	s_cmp_eq_u64 s[80:81], 0
	global_store_dwordx4 v[104:105], v[90:93], off
	s_cbranch_scc1 .LBB0_689
	v_pk_mul_f32 v[104:105], v[82:83], v[90:91]
	v_pk_mul_f32 v[106:107], v[84:85], v[92:93]
	v_cvt_pk_bf16_f32 v104, v104, v105
	v_cvt_pk_bf16_f32 v105, v106, v107
	v_lshlrev_b64 v[106:107], 12, v[96:97]
	v_pk_mul_f32 v[90:91], v[90:91], v[90:91]
	v_pk_mul_f32 v[92:93], v[92:93], v[92:93]
	v_lshl_add_u64 v[106:107], s[20:21], 0, v[106:107]
	v_add_f32_e32 v0, v92, v93
	v_add_f32_e32 v90, v90, v91
	v_lshl_add_u64 v[106:107], v[94:95], 1, v[106:107]
	v_add_f32_e32 v0, v90, v0
	global_store_dwordx2 v[106:107], v[104:105], off
	s_nop 1
	v_mov_b32_dpp v90, v0 quad_perm:[1,0,3,2] row_mask:0xf bank_mask:0xf
	s_waitcnt lgkmcnt(0)
	v_add_f32_e32 v0, v0, v90
	s_nop 1
	v_mov_b32_dpp v90, v0 quad_perm:[2,3,0,1] row_mask:0xf bank_mask:0xf
	s_waitcnt lgkmcnt(0)
	v_add_f32_e32 v0, v0, v90
	s_nop 1
	v_mov_b32_dpp v90, v0 row_half_mirror row_mask:0xf bank_mask:0xf
	s_waitcnt lgkmcnt(0)
	v_add_f32_e32 v90, v0, v90
	s_nop 1
	v_mov_b32_dpp v91, v90 row_ror:8 row_mask:0xf bank_mask:0xf
	s_and_saveexec_b64 s[2:3], s[4:5]
	s_cbranch_execz .LBB0_688
	v_lshlrev_b64 v[92:93], 7, v[96:97]
	v_lshl_add_u64 v[92:93], s[42:43], 0, v[92:93]
	v_lshl_add_u64 v[92:93], s[0:1], 2, v[92:93]
	v_lshlrev_b32_e32 v0, 2, v139
	v_lshl_add_u64 v[92:93], v[92:93], 0, v[0:1]
	s_waitcnt lgkmcnt(0)
	v_add_f32_e32 v0, v90, v91
	global_store_dword v[92:93], v0, off

; DI void gemm_tile(const GD& g, int pm, int pn, bf16_t* shm) {
;     ...
;       for (int pb8 = 0; pb8 < 4; ++pb8) {
;         float4 xs[4];
;         if (g.epi == 1) {
; #pragma unroll
;           for (int q = 0; q < 4; ++q) {
;             const int grow = brow + ai * HALF + wr * 64 + (pb8 * 4 + q) * 4 + (lane >> 4);
;             xs[q] = *reinterpret_cast<const float4*>((const float*)g.C + (long)grow * ldc + gcol);
;           }
;         }
.LBB0_745:
	v_or_b32_e32 v0, 32, v99
	v_mad_u64_u32 v[4:5], s[2:3], v0, s78, 0
	v_or_b32_e32 v0, 36, v99
	v_mad_u64_u32 v[6:7], s[2:3], v0, s78, 0
	v_lshl_add_u64 v[2:3], v[94:95], 2, s[34:35]
	v_add_u32_e32 v5, v5, v102
	v_add_u32_e32 v7, v7, v102
	v_lshl_add_u64 v[4:5], v[4:5], 2, v[2:3]
	v_lshl_add_u64 v[6:7], v[6:7], 2, v[2:3]
	v_or_b32_e32 v0, 40, v99
	s_nop 0
	v_mad_u64_u32 v[4:5], s[2:3], v0, s78, 0
	v_or_b32_e32 v0, 44, v99
	v_mad_u64_u32 v[10:11], s[2:3], v0, s78, 0
	v_add_u32_e32 v5, v5, v102
	v_add_u32_e32 v11, v11, v102
	v_lshl_add_u64 v[4:5], v[4:5], 2, v[2:3]
	v_lshl_add_u64 v[2:3], v[10:11], 2, v[2:3]
	s_nop 0
	s_waitcnt vmcnt(12)
	v_mov_b64_e32 v[14:15], v[124:125]
	v_mov_b64_e32 v[16:17], v[126:127]
	v_mov_b64_e32 v[6:7], v[156:157]
	v_mov_b64_e32 v[8:9], v[158:159]
	v_mov_b64_e32 v[10:11], v[160:161]
	v_mov_b64_e32 v[12:13], v[162:163]
	v_mov_b64_e32 v[2:3], v[164:165]
	v_mov_b64_e32 v[4:5], v[166:167]

; DI void gemm_tile(const GD& g, int pm, int pn, bf16_t* shm) {
;     ...
;       for (int pb8 = 0; pb8 < 4; ++pb8) {
;         float4 xs[4];
;         if (g.epi == 1) {
; #pragma unroll
;           for (int q = 0; q < 4; ++q) {
;             const int grow = brow + ai * HALF + wr * 64 + (pb8 * 4 + q) * 4 + (lane >> 4);
;             xs[q] = *reinterpret_cast<const float4*>((const float*)g.C + (long)grow * ldc + gcol);
;           }
;         }
.LBB0_811:
	v_or_b32_e32 v0, 48, v99
	v_mad_u64_u32 v[4:5], s[2:3], v0, s78, 0
	v_or_b32_e32 v0, 52, v99
	v_mad_u64_u32 v[6:7], s[2:3], v0, s78, 0
	v_lshl_add_u64 v[2:3], v[94:95], 2, s[34:35]
	v_add_u32_e32 v5, v5, v102
	v_add_u32_e32 v7, v7, v102
	v_lshl_add_u64 v[4:5], v[4:5], 2, v[2:3]
	v_lshl_add_u64 v[6:7], v[6:7], 2, v[2:3]
	v_or_b32_e32 v0, 56, v99
	s_nop 0
	v_mad_u64_u32 v[4:5], s[2:3], v0, s78, 0
	v_or_b32_e32 v0, 60, v99
	v_mad_u64_u32 v[10:11], s[2:3], v0, s78, 0
	v_add_u32_e32 v5, v5, v102
	v_add_u32_e32 v11, v11, v102
	v_lshl_add_u64 v[4:5], v[4:5], 2, v[2:3]
	v_lshl_add_u64 v[2:3], v[10:11], 2, v[2:3]
	s_nop 0
	s_waitcnt vmcnt(12)
	v_mov_b64_e32 v[14:15], v[168:169]
	v_mov_b64_e32 v[16:17], v[170:171]
	v_mov_b64_e32 v[6:7], v[172:173]
	v_mov_b64_e32 v[8:9], v[174:175]
	v_mov_b64_e32 v[10:11], v[176:177]
	v_mov_b64_e32 v[12:13], v[178:179]
	v_mov_b64_e32 v[2:3], v[180:181]
	v_mov_b64_e32 v[4:5], v[182:183]

; DI unsigned pk2(float a, float b) { f32x2 v; v[0] = a; v[1] = b; return __builtin_bit_cast(unsigned, __builtin_convertvector(v, bf16v2)); }
; DI float shx_(float v, int m) { return __int_as_float(__builtin_amdgcn_ds_bpermute((lane_pinned_() ^ m) << 2, __float_as_int(v))); }
; DI int shx_(int v, int m) { return __builtin_amdgcn_ds_bpermute((lane_pinned_() ^ m) << 2, v); }
; DI void gemm_tile(const GD& g, int pm, int pn, bf16_t* shm) {
;     ...
;         for (int q = 0; q < 4; ++q) {
;           const int row_l = (pb8 * 4 + q) * 4 + (lane >> 4);
;           float4 v = *reinterpret_cast<const float4*>(stgw + row_l * 68 + c4);
;           const int grow = brow + ai * HALF + wr * 64 + row_l;
;           if (g.epi == 0) {
;             if (g.rowscale) {
;               const float rr = rsc[ai * HALF + wr * 64 + row_l];
;               v.x *= rr; v.y *= rr; v.z *= rr; v.w *= rr;
;             }
;             u32x2 o2; o2[0] = pk2(v.x, v.y); o2[1] = pk2(v.z, v.w);
;             *reinterpret_cast<u32x2*>((bf16_t*)g.C + (long)grow * ldc + gcol) = o2;
;           } else if (g.epi == 2) {
;             const float rr = rsc[ai * HALF + wr * 64 + row_l];
;             v.x *= rr; v.y *= rr; v.z *= rr; v.w *= rr;
;             *reinterpret_cast<float4*>((float*)g.C + (long)grow * ldc + gcol) = v;
;           } else {
;             float4 x = xs[q];
;             x.x += v.x; x.y += v.y; x.z += v.z; x.w += v.w;
;             *reinterpret_cast<float4*>((float*)g.C + (long)grow * ldc + gcol) = x;
;             if (g.gnext) {
;               u32x2 o2; o2[0] = pk2(x.x * gn.x, x.y * gn.y); o2[1] = pk2(x.z * gn.z, x.w * gn.w);
;               *reinterpret_cast<u32x2*>(g.hbout + (long)grow * DM + gcol) = o2;
;               float sq = (x.x * x.x + x.y * x.y) + (x.z * x.z + x.w * x.w);
;               sq += shx_(sq, 1); sq += shx_(sq, 2); sq += shx_(sq, 4); sq += shx_(sq, 8);
;               if ((lane & 15) == 0) g.ss[(long)grow * 32 + pn * 4 + wc] = sq;
;             }
.LBB0_817:
	v_mad_u64_u32 v[102:103], s[2:3], v96, s78, 0
	v_mov_b32_e32 v0, v103
	v_mad_u64_u32 v[104:105], s[2:3], v97, s78, v[0:1]
	v_mov_b32_e32 v103, v104
	v_lshl_add_u64 v[102:103], v[102:103], 2, s[34:35]
	s_waitcnt lgkmcnt(0)
	v_pk_add_f32 v[90:91], v[14:15], v[86:87]
	v_pk_add_f32 v[92:93], v[16:17], v[88:89]
	v_lshl_add_u64 v[102:103], v[94:95], 2, v[102:103]
	s_cmp_eq_u64 s[80:81], 0
	global_store_dwordx4 v[102:103], v[90:93], off
	s_cbranch_scc1 .LBB0_821
	v_pk_mul_f32 v[102:103], v[82:83], v[90:91]
	v_pk_mul_f32 v[104:105], v[84:85], v[92:93]
	v_cvt_pk_bf16_f32 v102, v102, v103
	v_cvt_pk_bf16_f32 v103, v104, v105
	v_lshlrev_b64 v[104:105], 12, v[96:97]
	v_pk_mul_f32 v[90:91], v[90:91], v[90:91]
	v_pk_mul_f32 v[92:93], v[92:93], v[92:93]
	v_lshl_add_u64 v[104:105], s[20:21], 0, v[104:105]
	v_add_f32_e32 v0, v92, v93
	v_add_f32_e32 v90, v90, v91
	v_lshl_add_u64 v[104:105], v[94:95], 1, v[104:105]
	v_add_f32_e32 v0, v90, v0
	global_store_dwordx2 v[104:105], v[102:103], off
	s_nop 1
	v_mov_b32_dpp v90, v0 quad_perm:[1,0,3,2] row_mask:0xf bank_mask:0xf
	s_waitcnt lgkmcnt(0)
	v_add_f32_e32 v0, v0, v90
	s_nop 1
	v_mov_b32_dpp v90, v0 quad_perm:[2,3,0,1] row_mask:0xf bank_mask:0xf
	s_waitcnt lgkmcnt(0)
	v_add_f32_e32 v0, v0, v90
	s_nop 1
	v_mov_b32_dpp v90, v0 row_half_mirror row_mask:0xf bank_mask:0xf
	s_waitcnt lgkmcnt(0)
	v_add_f32_e32 v90, v0, v90
	s_nop 1
	v_mov_b32_dpp v91, v90 row_ror:8 row_mask:0xf bank_mask:0xf
	s_and_saveexec_b64 s[2:3], s[4:5]
	s_cbranch_execz .LBB0_820
	v_lshlrev_b64 v[92:93], 7, v[96:97]
	v_lshl_add_u64 v[92:93], s[42:43], 0, v[92:93]
	v_lshl_add_u64 v[92:93], s[0:1], 2, v[92:93]
	v_lshlrev_b32_e32 v0, 2, v139
	v_lshl_add_u64 v[92:93], v[92:93], 0, v[0:1]
	s_waitcnt lgkmcnt(0)
	v_add_f32_e32 v0, v90, v91
	global_store_dword v[92:93], v0, off

; DI void gemm_tile(const GD& g, int pm, int pn, bf16_t* shm) {
;     ...
;       for (int pb8 = 0; pb8 < 4; ++pb8) {
;         float4 xs[4];
;         if (g.epi == 1) {
; #pragma unroll
;           for (int q = 0; q < 4; ++q) {
;             const int grow = brow + ai * HALF + wr * 64 + (pb8 * 4 + q) * 4 + (lane >> 4);
;             xs[q] = *reinterpret_cast<const float4*>((const float*)g.C + (long)grow * ldc + gcol);
;           }
;         }
.LBB0_1027:
	s_andn2_b64 vcc, exec, s[2:3]
	s_cbranch_vccnz .LBB0_1292
	s_cmp_eq_u32 s48, 1
	s_cselect_b64 s[10:11], -1, 0
	s_cmp_lg_u32 s48, 1
	v_lshl_add_u64 v[30:31], v[94:95], 2, s[34:35]
	s_cbranch_scc1 .LBB0_1030
	v_add_u32_e32 v0, 0x80, v99
	v_mad_u64_u32 v[2:3], s[2:3], v0, s78, 0
	v_ashrrev_i32_e32 v4, 31, v0
	v_mov_b32_e32 v0, v3
	v_mad_u64_u32 v[4:5], s[2:3], v4, s78, v[0:1]
	v_add_u32_e32 v0, 0x84, v99
	v_mov_b32_e32 v3, v4
	v_mad_u64_u32 v[4:5], s[2:3], v0, s78, 0
	v_ashrrev_i32_e32 v6, 31, v0
	v_mov_b32_e32 v0, v5
	v_mad_u64_u32 v[6:7], s[2:3], v6, s78, v[0:1]
	v_lshl_add_u64 v[2:3], v[2:3], 2, v[30:31]
	v_mov_b32_e32 v5, v6
	v_add_u32_e32 v0, 0x88, v99
	v_lshl_add_u64 v[4:5], v[4:5], 2, v[30:31]
	global_load_dwordx4 v[14:17], v[2:3], off
	global_load_dwordx4 v[6:9], v[4:5], off
	v_mad_u64_u32 v[2:3], s[2:3], v0, s78, 0
	v_ashrrev_i32_e32 v4, 31, v0
	v_mov_b32_e32 v0, v3
	v_mad_u64_u32 v[4:5], s[2:3], v4, s78, v[0:1]
	v_add_u32_e32 v0, 0x8c, v99
	v_mov_b32_e32 v3, v4
	v_mad_u64_u32 v[4:5], s[2:3], v0, s78, 0
	v_ashrrev_i32_e32 v10, 31, v0
	v_mov_b32_e32 v0, v5
	v_mad_u64_u32 v[10:11], s[2:3], v10, s78, v[0:1]
	v_mov_b32_e32 v5, v10
	v_lshl_add_u64 v[2:3], v[2:3], 2, v[30:31]
	v_lshl_add_u64 v[4:5], v[4:5], 2, v[30:31]
	global_load_dwordx4 v[10:13], v[2:3], off
	s_nop 0
	global_load_dwordx4 v[2:5], v[4:5], off
	v_lshl_add_u64 v[194:195], v[94:95], 2, s[34:35]
	v_add_u32_e32 v196, 144, v99
	v_mad_u64_u32 v[198:199], s[2:3], v196, s78, 0
	v_lshl_add_u64 v[198:199], v[198:199], 2, v[194:195]
	global_load_dwordx4 v[108:111], v[198:199], off
	v_add_u32_e32 v196, 148, v99
	v_mad_u64_u32 v[198:199], s[2:3], v196, s78, 0
	v_lshl_add_u64 v[198:199], v[198:199], 2, v[194:195]
	global_load_dwordx4 v[112:115], v[198:199], off
	v_add_u32_e32 v196, 152, v99
	v_mad_u64_u32 v[198:199], s[2:3], v196, s78, 0
	v_lshl_add_u64 v[198:199], v[198:199], 2, v[194:195]
	global_load_dwordx4 v[116:119], v[198:199], off
	v_add_u32_e32 v196, 156, v99
	v_mad_u64_u32 v[198:199], s[2:3], v196, s78, 0
	v_lshl_add_u64 v[198:199], v[198:199], 2, v[194:195]
	global_load_dwordx4 v[120:123], v[198:199], off
	v_add_u32_e32 v196, 160, v99
	v_mad_u64_u32 v[198:199], s[2:3], v196, s78, 0
	v_lshl_add_u64 v[198:199], v[198:199], 2, v[194:195]
	global_load_dwordx4 v[124:127], v[198:199], off
	v_add_u32_e32 v196, 164, v99
	v_mad_u64_u32 v[198:199], s[2:3], v196, s78, 0
	v_lshl_add_u64 v[198:199], v[198:199], 2, v[194:195]
	global_load_dwordx4 v[156:159], v[198:199], off
	v_add_u32_e32 v196, 168, v99
	v_mad_u64_u32 v[198:199], s[2:3], v196, s78, 0
	v_lshl_add_u64 v[198:199], v[198:199], 2, v[194:195]
	global_load_dwordx4 v[160:163], v[198:199], off
	v_add_u32_e32 v196, 172, v99
	v_mad_u64_u32 v[198:199], s[2:3], v196, s78, 0
	v_lshl_add_u64 v[198:199], v[198:199], 2, v[194:195]
	global_load_dwordx4 v[164:167], v[198:199], off
	v_add_u32_e32 v196, 176, v99
	v_mad_u64_u32 v[198:199], s[2:3], v196, s78, 0
	v_lshl_add_u64 v[198:199], v[198:199], 2, v[194:195]
	global_load_dwordx4 v[168:171], v[198:199], off
	v_add_u32_e32 v196, 180, v99
	v_mad_u64_u32 v[198:199], s[2:3], v196, s78, 0
	v_lshl_add_u64 v[198:199], v[198:199], 2, v[194:195]
	global_load_dwordx4 v[172:175], v[198:199], off
	v_add_u32_e32 v196, 184, v99
	v_mad_u64_u32 v[198:199], s[2:3], v196, s78, 0
	v_lshl_add_u64 v[198:199], v[198:199], 2, v[194:195]
	global_load_dwordx4 v[176:179], v[198:199], off
	v_add_u32_e32 v196, 188, v99
	v_mad_u64_u32 v[198:199], s[2:3], v196, s78, 0
	v_lshl_add_u64 v[198:199], v[198:199], 2, v[194:195]
	global_load_dwordx4 v[180:183], v[198:199], off

; DI unsigned pk2(float a, float b) { f32x2 v; v[0] = a; v[1] = b; return __builtin_bit_cast(unsigned, __builtin_convertvector(v, bf16v2)); }
; DI float shx_(float v, int m) { return __int_as_float(__builtin_amdgcn_ds_bpermute((lane_pinned_() ^ m) << 2, __float_as_int(v))); }
; DI int shx_(int v, int m) { return __builtin_amdgcn_ds_bpermute((lane_pinned_() ^ m) << 2, v); }
; DI void gemm_tile(const GD& g, int pm, int pn, bf16_t* shm) {
;     ...
;         for (int q = 0; q < 4; ++q) {
;           const int row_l = (pb8 * 4 + q) * 4 + (lane >> 4);
;           float4 v = *reinterpret_cast<const float4*>(stgw + row_l * 68 + c4);
;           const int grow = brow + ai * HALF + wr * 64 + row_l;
;           if (g.epi == 0) {
;             if (g.rowscale) {
;               const float rr = rsc[ai * HALF + wr * 64 + row_l];
;               v.x *= rr; v.y *= rr; v.z *= rr; v.w *= rr;
;             }
;             u32x2 o2; o2[0] = pk2(v.x, v.y); o2[1] = pk2(v.z, v.w);
;             *reinterpret_cast<u32x2*>((bf16_t*)g.C + (long)grow * ldc + gcol) = o2;
;           } else if (g.epi == 2) {
;             const float rr = rsc[ai * HALF + wr * 64 + row_l];
;             v.x *= rr; v.y *= rr; v.z *= rr; v.w *= rr;
;             *reinterpret_cast<float4*>((float*)g.C + (long)grow * ldc + gcol) = v;
;           } else {
;             float4 x = xs[q];
;             x.x += v.x; x.y += v.y; x.z += v.z; x.w += v.w;
;             *reinterpret_cast<float4*>((float*)g.C + (long)grow * ldc + gcol) = x;
;             if (g.gnext) {
;               u32x2 o2; o2[0] = pk2(x.x * gn.x, x.y * gn.y); o2[1] = pk2(x.z * gn.z, x.w * gn.w);
;               *reinterpret_cast<u32x2*>(g.hbout + (long)grow * DM + gcol) = o2;
;               float sq = (x.x * x.x + x.y * x.y) + (x.z * x.z + x.w * x.w);
;               sq += shx_(sq, 1); sq += shx_(sq, 2); sq += shx_(sq, 4); sq += shx_(sq, 8);
;               if ((lane & 15) == 0) g.ss[(long)grow * 32 + pn * 4 + wc] = sq;
;             }
.LBB0_1035:
	v_mad_u64_u32 v[36:37], s[2:3], v32, s78, 0
	v_mov_b32_e32 v0, v37
	v_mad_u64_u32 v[38:39], s[2:3], v33, s78, v[0:1]
	v_mov_b32_e32 v37, v38
	v_lshl_add_u64 v[36:37], v[36:37], 2, s[34:35]
	s_waitcnt vmcnt(12) lgkmcnt(0)
	v_pk_add_f32 v[26:27], v[14:15], v[22:23]
	v_pk_add_f32 v[28:29], v[16:17], v[24:25]
	v_lshl_add_u64 v[36:37], v[94:95], 2, v[36:37]
	s_cmp_eq_u64 s[80:81], 0
	global_store_dwordx4 v[36:37], v[26:29], off
	s_cbranch_scc1 .LBB0_1039
	v_pk_mul_f32 v[36:37], v[18:19], v[26:27]
	v_pk_mul_f32 v[38:39], v[20:21], v[28:29]
	v_cvt_pk_bf16_f32 v36, v36, v37
	v_cvt_pk_bf16_f32 v37, v38, v39
	v_lshlrev_b64 v[38:39], 12, v[32:33]
	v_pk_mul_f32 v[26:27], v[26:27], v[26:27]
	v_pk_mul_f32 v[28:29], v[28:29], v[28:29]
	v_lshl_add_u64 v[38:39], s[20:21], 0, v[38:39]
	v_add_f32_e32 v0, v28, v29
	v_add_f32_e32 v26, v26, v27
	v_lshl_add_u64 v[38:39], v[94:95], 1, v[38:39]
	v_add_f32_e32 v0, v26, v0
	global_store_dwordx2 v[38:39], v[36:37], off
	s_nop 1
	v_mov_b32_dpp v26, v0 quad_perm:[1,0,3,2] row_mask:0xf bank_mask:0xf
	s_waitcnt lgkmcnt(0)
	v_add_f32_e32 v0, v0, v26
	s_nop 1
	v_mov_b32_dpp v26, v0 quad_perm:[2,3,0,1] row_mask:0xf bank_mask:0xf
	s_waitcnt lgkmcnt(0)
	v_add_f32_e32 v0, v0, v26
	s_nop 1
	v_mov_b32_dpp v26, v0 row_half_mirror row_mask:0xf bank_mask:0xf
	s_waitcnt lgkmcnt(0)
	v_add_f32_e32 v26, v0, v26
	s_nop 1
	v_mov_b32_dpp v27, v26 row_ror:8 row_mask:0xf bank_mask:0xf
	s_and_saveexec_b64 s[2:3], s[4:5]
	s_cbranch_execz .LBB0_1038
	v_lshlrev_b64 v[28:29], 7, v[32:33]
	v_lshl_add_u64 v[28:29], s[42:43], 0, v[28:29]
	v_lshl_add_u64 v[28:29], s[0:1], 2, v[28:29]
	v_lshlrev_b32_e32 v0, 2, v139
	v_lshl_add_u64 v[28:29], v[28:29], 0, v[0:1]
	s_waitcnt lgkmcnt(0)
	v_add_f32_e32 v0, v26, v27
	global_store_dword v[28:29], v0, off

; DI void gemm_tile(const GD& g, int pm, int pn, bf16_t* shm) {
;     ...
;       for (int pb8 = 0; pb8 < 4; ++pb8) {
;         float4 xs[4];
;         if (g.epi == 1) {
; #pragma unroll
;           for (int q = 0; q < 4; ++q) {
;             const int grow = brow + ai * HALF + wr * 64 + (pb8 * 4 + q) * 4 + (lane >> 4);
;             xs[q] = *reinterpret_cast<const float4*>((const float*)g.C + (long)grow * ldc + gcol);
;           }
;         }
.LBB0_1089:
	v_add_u32_e32 v0, 0x90, v99
	v_mad_u64_u32 v[2:3], s[2:3], v0, s78, 0
	v_ashrrev_i32_e32 v4, 31, v0
	v_mov_b32_e32 v0, v3
	v_mad_u64_u32 v[4:5], s[2:3], v4, s78, v[0:1]
	v_add_u32_e32 v0, 0x94, v99
	v_mov_b32_e32 v3, v4
	v_mad_u64_u32 v[4:5], s[2:3], v0, s78, 0
	v_ashrrev_i32_e32 v6, 31, v0
	v_mov_b32_e32 v0, v5
	v_mad_u64_u32 v[6:7], s[2:3], v6, s78, v[0:1]
	v_lshl_add_u64 v[2:3], v[2:3], 2, v[30:31]
	v_mov_b32_e32 v5, v6
	v_add_u32_e32 v0, 0x98, v99
	v_lshl_add_u64 v[4:5], v[4:5], 2, v[30:31]
	v_mad_u64_u32 v[2:3], s[2:3], v0, s78, 0
	v_ashrrev_i32_e32 v4, 31, v0
	v_mov_b32_e32 v0, v3
	v_mad_u64_u32 v[4:5], s[2:3], v4, s78, v[0:1]
	v_add_u32_e32 v0, 0x9c, v99
	v_mov_b32_e32 v3, v4
	v_mad_u64_u32 v[4:5], s[2:3], v0, s78, 0
	v_ashrrev_i32_e32 v10, 31, v0
	v_mov_b32_e32 v0, v5
	v_mad_u64_u32 v[10:11], s[2:3], v10, s78, v[0:1]
	v_mov_b32_e32 v5, v10
	v_lshl_add_u64 v[2:3], v[2:3], 2, v[30:31]
	v_lshl_add_u64 v[4:5], v[4:5], 2, v[30:31]
	s_nop 0
	s_waitcnt vmcnt(12)
	v_mov_b64_e32 v[14:15], v[108:109]
	v_mov_b64_e32 v[16:17], v[110:111]
	v_mov_b64_e32 v[6:7], v[112:113]
	v_mov_b64_e32 v[8:9], v[114:115]
	v_mov_b64_e32 v[10:11], v[116:117]
	v_mov_b64_e32 v[12:13], v[118:119]
	v_mov_b64_e32 v[2:3], v[120:121]
	v_mov_b64_e32 v[4:5], v[122:123]

; DI unsigned pk2(float a, float b) { f32x2 v; v[0] = a; v[1] = b; return __builtin_bit_cast(unsigned, __builtin_convertvector(v, bf16v2)); }
; DI float shx_(float v, int m) { return __int_as_float(__builtin_amdgcn_ds_bpermute((lane_pinned_() ^ m) << 2, __float_as_int(v))); }
; DI int shx_(int v, int m) { return __builtin_amdgcn_ds_bpermute((lane_pinned_() ^ m) << 2, v); }
; DI void gemm_tile(const GD& g, int pm, int pn, bf16_t* shm) {
;     ...
;         for (int q = 0; q < 4; ++q) {
;           const int row_l = (pb8 * 4 + q) * 4 + (lane >> 4);
;           float4 v = *reinterpret_cast<const float4*>(stgw + row_l * 68 + c4);
;           const int grow = brow + ai * HALF + wr * 64 + row_l;
;           if (g.epi == 0) {
;             if (g.rowscale) {
;               const float rr = rsc[ai * HALF + wr * 64 + row_l];
;               v.x *= rr; v.y *= rr; v.z *= rr; v.w *= rr;
;             }
;             u32x2 o2; o2[0] = pk2(v.x, v.y); o2[1] = pk2(v.z, v.w);
;             *reinterpret_cast<u32x2*>((bf16_t*)g.C + (long)grow * ldc + gcol) = o2;
;           } else if (g.epi == 2) {
;             const float rr = rsc[ai * HALF + wr * 64 + row_l];
;             v.x *= rr; v.y *= rr; v.z *= rr; v.w *= rr;
;             *reinterpret_cast<float4*>((float*)g.C + (long)grow * ldc + gcol) = v;
;           } else {
;             float4 x = xs[q];
;             x.x += v.x; x.y += v.y; x.z += v.z; x.w += v.w;
;             *reinterpret_cast<float4*>((float*)g.C + (long)grow * ldc + gcol) = x;
;             if (g.gnext) {
;               u32x2 o2; o2[0] = pk2(x.x * gn.x, x.y * gn.y); o2[1] = pk2(x.z * gn.z, x.w * gn.w);
;               *reinterpret_cast<u32x2*>(g.hbout + (long)grow * DM + gcol) = o2;
;               float sq = (x.x * x.x + x.y * x.y) + (x.z * x.z + x.w * x.w);
;               sq += shx_(sq, 1); sq += shx_(sq, 2); sq += shx_(sq, 4); sq += shx_(sq, 8);
;               if ((lane & 15) == 0) g.ss[(long)grow * 32 + pn * 4 + wc] = sq;
;             }
.LBB0_1095:
	v_mad_u64_u32 v[36:37], s[2:3], v32, s78, 0
	v_mov_b32_e32 v0, v37
	v_mad_u64_u32 v[38:39], s[2:3], v33, s78, v[0:1]
	v_mov_b32_e32 v37, v38
	v_lshl_add_u64 v[36:37], v[36:37], 2, s[34:35]
	s_waitcnt lgkmcnt(0)
	v_pk_add_f32 v[26:27], v[14:15], v[22:23]
	v_pk_add_f32 v[28:29], v[16:17], v[24:25]
	v_lshl_add_u64 v[36:37], v[94:95], 2, v[36:37]
	s_cmp_eq_u64 s[80:81], 0
	global_store_dwordx4 v[36:37], v[26:29], off
	s_cbranch_scc1 .LBB0_1099
	v_pk_mul_f32 v[36:37], v[18:19], v[26:27]
	v_pk_mul_f32 v[38:39], v[20:21], v[28:29]
	v_cvt_pk_bf16_f32 v36, v36, v37
	v_cvt_pk_bf16_f32 v37, v38, v39
	v_lshlrev_b64 v[38:39], 12, v[32:33]
	v_pk_mul_f32 v[26:27], v[26:27], v[26:27]
	v_pk_mul_f32 v[28:29], v[28:29], v[28:29]
	v_lshl_add_u64 v[38:39], s[20:21], 0, v[38:39]
	v_add_f32_e32 v0, v28, v29
	v_add_f32_e32 v26, v26, v27
	v_lshl_add_u64 v[38:39], v[94:95], 1, v[38:39]
	v_add_f32_e32 v0, v26, v0
	global_store_dwordx2 v[38:39], v[36:37], off
	s_nop 1
	v_mov_b32_dpp v26, v0 quad_perm:[1,0,3,2] row_mask:0xf bank_mask:0xf
	s_waitcnt lgkmcnt(0)
	v_add_f32_e32 v0, v0, v26
	s_nop 1
	v_mov_b32_dpp v26, v0 quad_perm:[2,3,0,1] row_mask:0xf bank_mask:0xf
	s_waitcnt lgkmcnt(0)
	v_add_f32_e32 v0, v0, v26
	s_nop 1
	v_mov_b32_dpp v26, v0 row_half_mirror row_mask:0xf bank_mask:0xf
	s_waitcnt lgkmcnt(0)
	v_add_f32_e32 v26, v0, v26
	s_nop 1
	v_mov_b32_dpp v27, v26 row_ror:8 row_mask:0xf bank_mask:0xf
	s_and_saveexec_b64 s[2:3], s[4:5]
	s_cbranch_execz .LBB0_1098
	v_lshlrev_b64 v[28:29], 7, v[32:33]
	v_lshl_add_u64 v[28:29], s[42:43], 0, v[28:29]
	v_lshl_add_u64 v[28:29], s[0:1], 2, v[28:29]
	v_lshlrev_b32_e32 v0, 2, v139
	v_lshl_add_u64 v[28:29], v[28:29], 0, v[0:1]
	s_waitcnt lgkmcnt(0)
	v_add_f32_e32 v0, v26, v27
	global_store_dword v[28:29], v0, off

; DI void gemm_tile(const GD& g, int pm, int pn, bf16_t* shm) {
;     ...
;       for (int pb8 = 0; pb8 < 4; ++pb8) {
;         float4 xs[4];
;         if (g.epi == 1) {
; #pragma unroll
;           for (int q = 0; q < 4; ++q) {
;             const int grow = brow + ai * HALF + wr * 64 + (pb8 * 4 + q) * 4 + (lane >> 4);
;             xs[q] = *reinterpret_cast<const float4*>((const float*)g.C + (long)grow * ldc + gcol);
;           }
;         }
.LBB0_1155:
	v_add_u32_e32 v0, 0xa0, v99
	v_mad_u64_u32 v[2:3], s[2:3], v0, s78, 0
	v_ashrrev_i32_e32 v4, 31, v0
	v_mov_b32_e32 v0, v3
	v_mad_u64_u32 v[4:5], s[2:3], v4, s78, v[0:1]
	v_add_u32_e32 v0, 0xa4, v99
	v_mov_b32_e32 v3, v4
	v_mad_u64_u32 v[4:5], s[2:3], v0, s78, 0
	v_ashrrev_i32_e32 v6, 31, v0
	v_mov_b32_e32 v0, v5
	v_mad_u64_u32 v[6:7], s[2:3], v6, s78, v[0:1]
	v_lshl_add_u64 v[2:3], v[2:3], 2, v[30:31]
	v_mov_b32_e32 v5, v6
	v_add_u32_e32 v0, 0xa8, v99
	v_lshl_add_u64 v[4:5], v[4:5], 2, v[30:31]
	v_mad_u64_u32 v[2:3], s[2:3], v0, s78, 0
	v_ashrrev_i32_e32 v4, 31, v0
	v_mov_b32_e32 v0, v3
	v_mad_u64_u32 v[4:5], s[2:3], v4, s78, v[0:1]
	v_add_u32_e32 v0, 0xac, v99
	v_mov_b32_e32 v3, v4
	v_mad_u64_u32 v[4:5], s[2:3], v0, s78, 0
	v_ashrrev_i32_e32 v10, 31, v0
	v_mov_b32_e32 v0, v5
	v_mad_u64_u32 v[10:11], s[2:3], v10, s78, v[0:1]
	v_mov_b32_e32 v5, v10
	v_lshl_add_u64 v[2:3], v[2:3], 2, v[30:31]
	v_lshl_add_u64 v[4:5], v[4:5], 2, v[30:31]
	s_nop 0
	s_waitcnt vmcnt(12)
	v_mov_b64_e32 v[14:15], v[124:125]
	v_mov_b64_e32 v[16:17], v[126:127]
	v_mov_b64_e32 v[6:7], v[156:157]
	v_mov_b64_e32 v[8:9], v[158:159]
	v_mov_b64_e32 v[10:11], v[160:161]
	v_mov_b64_e32 v[12:13], v[162:163]
	v_mov_b64_e32 v[2:3], v[164:165]
	v_mov_b64_e32 v[4:5], v[166:167]

; DI void gemm_tile(const GD& g, int pm, int pn, bf16_t* shm) {
;     ...
;       for (int pb8 = 0; pb8 < 4; ++pb8) {
;         float4 xs[4];
;         if (g.epi == 1) {
; #pragma unroll
;           for (int q = 0; q < 4; ++q) {
;             const int grow = brow + ai * HALF + wr * 64 + (pb8 * 4 + q) * 4 + (lane >> 4);
;             xs[q] = *reinterpret_cast<const float4*>((const float*)g.C + (long)grow * ldc + gcol);
;           }
;         }
.LBB0_1221:
	v_add_u32_e32 v0, 0xb0, v99
	v_mad_u64_u32 v[2:3], s[2:3], v0, s78, 0
	v_ashrrev_i32_e32 v4, 31, v0
	v_mov_b32_e32 v0, v3
	v_mad_u64_u32 v[4:5], s[2:3], v4, s78, v[0:1]
	v_add_u32_e32 v0, 0xb4, v99
	v_mov_b32_e32 v3, v4
	v_mad_u64_u32 v[4:5], s[2:3], v0, s78, 0
	v_ashrrev_i32_e32 v6, 31, v0
	v_mov_b32_e32 v0, v5
	v_mad_u64_u32 v[6:7], s[2:3], v6, s78, v[0:1]
	v_lshl_add_u64 v[2:3], v[2:3], 2, v[30:31]
	v_mov_b32_e32 v5, v6
	v_add_u32_e32 v0, 0xb8, v99
	v_lshl_add_u64 v[4:5], v[4:5], 2, v[30:31]
	v_mad_u64_u32 v[2:3], s[2:3], v0, s78, 0
	v_ashrrev_i32_e32 v4, 31, v0
	v_mov_b32_e32 v0, v3
	v_mad_u64_u32 v[4:5], s[2:3], v4, s78, v[0:1]
	v_add_u32_e32 v0, 0xbc, v99
	v_mov_b32_e32 v3, v4
	v_mad_u64_u32 v[4:5], s[2:3], v0, s78, 0
	v_ashrrev_i32_e32 v10, 31, v0
	v_mov_b32_e32 v0, v5
	v_mad_u64_u32 v[10:11], s[2:3], v10, s78, v[0:1]
	v_mov_b32_e32 v5, v10
	v_lshl_add_u64 v[2:3], v[2:3], 2, v[30:31]
	v_lshl_add_u64 v[4:5], v[4:5], 2, v[30:31]
	s_nop 0
	s_waitcnt vmcnt(12)
	v_mov_b64_e32 v[14:15], v[168:169]
	v_mov_b64_e32 v[16:17], v[170:171]
	v_mov_b64_e32 v[6:7], v[172:173]
	v_mov_b64_e32 v[8:9], v[174:175]
	v_mov_b64_e32 v[10:11], v[176:177]
	v_mov_b64_e32 v[12:13], v[178:179]
	v_mov_b64_e32 v[2:3], v[180:181]
	v_mov_b64_e32 v[4:5], v[182:183]

; DI unsigned pk2(float a, float b) { f32x2 v; v[0] = a; v[1] = b; return __builtin_bit_cast(unsigned, __builtin_convertvector(v, bf16v2)); }
; DI float shx_(float v, int m) { return __int_as_float(__builtin_amdgcn_ds_bpermute((lane_pinned_() ^ m) << 2, __float_as_int(v))); }
; DI int shx_(int v, int m) { return __builtin_amdgcn_ds_bpermute((lane_pinned_() ^ m) << 2, v); }
; DI void gemm_tile(const GD& g, int pm, int pn, bf16_t* shm) {
;     ...
;         for (int q = 0; q < 4; ++q) {
;           const int row_l = (pb8 * 4 + q) * 4 + (lane >> 4);
;           float4 v = *reinterpret_cast<const float4*>(stgw + row_l * 68 + c4);
;           const int grow = brow + ai * HALF + wr * 64 + row_l;
;           if (g.epi == 0) {
;             if (g.rowscale) {
;               const float rr = rsc[ai * HALF + wr * 64 + row_l];
;               v.x *= rr; v.y *= rr; v.z *= rr; v.w *= rr;
;             }
;             u32x2 o2; o2[0] = pk2(v.x, v.y); o2[1] = pk2(v.z, v.w);
;             *reinterpret_cast<u32x2*>((bf16_t*)g.C + (long)grow * ldc + gcol) = o2;
;           } else if (g.epi == 2) {
;             const float rr = rsc[ai * HALF + wr * 64 + row_l];
;             v.x *= rr; v.y *= rr; v.z *= rr; v.w *= rr;
;             *reinterpret_cast<float4*>((float*)g.C + (long)grow * ldc + gcol) = v;
;           } else {
;             float4 x = xs[q];
;             x.x += v.x; x.y += v.y; x.z += v.z; x.w += v.w;
;             *reinterpret_cast<float4*>((float*)g.C + (long)grow * ldc + gcol) = x;
;             if (g.gnext) {
;               u32x2 o2; o2[0] = pk2(x.x * gn.x, x.y * gn.y); o2[1] = pk2(x.z * gn.z, x.w * gn.w);
;               *reinterpret_cast<u32x2*>(g.hbout + (long)grow * DM + gcol) = o2;
;               float sq = (x.x * x.x + x.y * x.y) + (x.z * x.z + x.w * x.w);
;               sq += shx_(sq, 1); sq += shx_(sq, 2); sq += shx_(sq, 4); sq += shx_(sq, 8);
;               if ((lane & 15) == 0) g.ss[(long)grow * 32 + pn * 4 + wc] = sq;
;             }
.LBB0_1227:
	v_mad_u64_u32 v[28:29], s[2:3], v26, s78, 0
	v_mov_b32_e32 v0, v29
	v_mad_u64_u32 v[30:31], s[2:3], v27, s78, v[0:1]
	v_mov_b32_e32 v29, v30
	v_lshl_add_u64 v[28:29], v[28:29], 2, s[34:35]
	s_waitcnt lgkmcnt(0)
	v_pk_add_f32 v[14:15], v[14:15], v[22:23]
	v_pk_add_f32 v[16:17], v[16:17], v[24:25]
	v_lshl_add_u64 v[28:29], v[94:95], 2, v[28:29]
	s_cmp_eq_u64 s[80:81], 0
	global_store_dwordx4 v[28:29], v[14:17], off
	s_cbranch_scc1 .LBB0_1231
	v_pk_mul_f32 v[28:29], v[18:19], v[14:15]
	v_pk_mul_f32 v[30:31], v[20:21], v[16:17]
	v_cvt_pk_bf16_f32 v28, v28, v29
	v_cvt_pk_bf16_f32 v29, v30, v31
	v_lshlrev_b64 v[30:31], 12, v[26:27]
	v_pk_mul_f32 v[14:15], v[14:15], v[14:15]
	v_pk_mul_f32 v[16:17], v[16:17], v[16:17]
	v_lshl_add_u64 v[30:31], s[20:21], 0, v[30:31]
	v_add_f32_e32 v0, v16, v17
	v_add_f32_e32 v14, v14, v15
	v_lshl_add_u64 v[30:31], v[94:95], 1, v[30:31]
	v_add_f32_e32 v0, v14, v0
	global_store_dwordx2 v[30:31], v[28:29], off
	s_nop 1
	v_mov_b32_dpp v14, v0 quad_perm:[1,0,3,2] row_mask:0xf bank_mask:0xf
	s_waitcnt lgkmcnt(0)
	v_add_f32_e32 v0, v0, v14
	s_nop 1
	v_mov_b32_dpp v14, v0 quad_perm:[2,3,0,1] row_mask:0xf bank_mask:0xf
	s_waitcnt lgkmcnt(0)
	v_add_f32_e32 v0, v0, v14
	s_nop 1
	v_mov_b32_dpp v14, v0 row_half_mirror row_mask:0xf bank_mask:0xf
	s_waitcnt lgkmcnt(0)
	v_add_f32_e32 v14, v0, v14
	s_nop 1
	v_mov_b32_dpp v15, v14 row_ror:8 row_mask:0xf bank_mask:0xf
	s_and_saveexec_b64 s[2:3], s[4:5]
	s_cbranch_execz .LBB0_1230
	v_lshlrev_b64 v[16:17], 7, v[26:27]
	v_lshl_add_u64 v[16:17], s[42:43], 0, v[16:17]
	v_lshl_add_u64 v[16:17], s[0:1], 2, v[16:17]
	v_lshlrev_b32_e32 v0, 2, v139
	v_lshl_add_u64 v[16:17], v[16:17], 0, v[0:1]
	s_waitcnt lgkmcnt(0)
	v_add_f32_e32 v0, v14, v15
	global_store_dword v[16:17], v0, off
